# v24 + P0 compression-bias partial sums loop hand-pipelined (pos by one per-lane load + readlane broadcast, 48 w1 loads in flight, same fma order)
# speedup vs baseline: 1.0013x; 1.0013x over previous
.LBB0_430:
	s_and_b32 s6, s5, 15
	s_lshl_b32 s7, s12, 2
	s_lshl_b32 s10, s6, 19
	s_and_b32 s7, s7, 0x700
	s_lshl_b32 s11, s6, 10
	s_ashr_i32 s6, s19, 7
	v_lshl_or_b32 v4, v1, 2, s7
	s_ashr_i32 s7, s6, 31
	s_lshl_b64 s[8:9], s[6:7], 23
	v_readlane_b32 s36, v251, 32
	s_or_b32 s8, s8, s10
	v_readlane_b32 s42, v251, 38
	v_readlane_b32 s43, v251, 39
	s_add_u32 s8, s42, s8
	s_addc_u32 s9, s43, s9
	s_mov_b64 s[22:23], s[8:9]
	v_lshl_add_u64 v[6:7], s[8:9], 0, v[4:5]
	s_lshl_b64 s[8:9], s[6:7], 14
	s_or_b32 s7, s8, s11
	s_add_u32 s8, s14, s7
	s_addc_u32 s9, s15, s9
	s_mov_b64 s[10:11], 0
	v_mov_b32_e32 v3, 0
	v_readlane_b32 s37, v251, 33
	v_readlane_b32 s38, v251, 34
	v_readlane_b32 s39, v251, 35
	v_readlane_b32 s40, v251, 36
	v_readlane_b32 s41, v251, 37
	v_readlane_b32 s44, v251, 40
	v_readlane_b32 s45, v251, 41
	v_readlane_b32 s46, v251, 42
	v_readlane_b32 s47, v251, 43
	v_readlane_b32 s48, v251, 44
	v_readlane_b32 s49, v251, 45
	v_readlane_b32 s50, v251, 46
	v_readlane_b32 s51, v251, 47
	v_lshlrev_b32_e32 v12, 4, v1
	s_add_u32 s22, s22, 0x1000
	s_addc_u32 s23, s23, 0
	global_load_dwordx4 v[8:11], v12, s[8:9] offset:-28
	global_load_dword v44, v4, s[22:23] offset:-4096
	global_load_dword v45, v4, s[22:23] offset:-2048
	global_load_dword v46, v4, s[22:23] offset:0
	global_load_dword v47, v4, s[22:23] offset:2048
	s_add_u32 s22, s22, 0x2000
	s_addc_u32 s23, s23, 0
	global_load_dword v48, v4, s[22:23] offset:-4096
	global_load_dword v49, v4, s[22:23] offset:-2048
	global_load_dword v50, v4, s[22:23] offset:0
	global_load_dword v51, v4, s[22:23] offset:2048
	s_add_u32 s22, s22, 0x2000
	s_addc_u32 s23, s23, 0
	global_load_dword v52, v4, s[22:23] offset:-4096
	global_load_dword v53, v4, s[22:23] offset:-2048
	global_load_dword v54, v4, s[22:23] offset:0
	global_load_dword v55, v4, s[22:23] offset:2048
	s_add_u32 s22, s22, 0x2000
	s_addc_u32 s23, s23, 0
	global_load_dword v56, v4, s[22:23] offset:-4096
	global_load_dword v57, v4, s[22:23] offset:-2048
	global_load_dword v58, v4, s[22:23] offset:0
	global_load_dword v59, v4, s[22:23] offset:2048
	s_add_u32 s22, s22, 0x2000
	s_addc_u32 s23, s23, 0
	global_load_dword v60, v4, s[22:23] offset:-4096
	global_load_dword v61, v4, s[22:23] offset:-2048
	global_load_dword v62, v4, s[22:23] offset:0
	global_load_dword v63, v4, s[22:23] offset:2048
	s_add_u32 s22, s22, 0x2000
	s_addc_u32 s23, s23, 0
	global_load_dword v64, v4, s[22:23] offset:-4096
	global_load_dword v65, v4, s[22:23] offset:-2048
	global_load_dword v66, v4, s[22:23] offset:0
	global_load_dword v67, v4, s[22:23] offset:2048
	s_add_u32 s22, s22, 0x2000
	s_addc_u32 s23, s23, 0
	global_load_dword v68, v4, s[22:23] offset:-4096
	global_load_dword v69, v4, s[22:23] offset:-2048
	global_load_dword v70, v4, s[22:23] offset:0
	global_load_dword v71, v4, s[22:23] offset:2048
	s_add_u32 s22, s22, 0x2000
	s_addc_u32 s23, s23, 0
	global_load_dword v72, v4, s[22:23] offset:-4096
	global_load_dword v73, v4, s[22:23] offset:-2048
	global_load_dword v74, v4, s[22:23] offset:0
	global_load_dword v75, v4, s[22:23] offset:2048
	s_add_u32 s22, s22, 0x2000
	s_addc_u32 s23, s23, 0
	global_load_dword v76, v4, s[22:23] offset:-4096
	global_load_dword v77, v4, s[22:23] offset:-2048
	global_load_dword v78, v4, s[22:23] offset:0
	global_load_dword v79, v4, s[22:23] offset:2048
	s_add_u32 s22, s22, 0x2000
	s_addc_u32 s23, s23, 0
	global_load_dword v80, v4, s[22:23] offset:-4096
	global_load_dword v81, v4, s[22:23] offset:-2048
	global_load_dword v82, v4, s[22:23] offset:0
	global_load_dword v83, v4, s[22:23] offset:2048
	s_add_u32 s22, s22, 0x2000
	s_addc_u32 s23, s23, 0
	global_load_dword v84, v4, s[22:23] offset:-4096
	global_load_dword v85, v4, s[22:23] offset:-2048
	global_load_dword v86, v4, s[22:23] offset:0
	global_load_dword v87, v4, s[22:23] offset:2048
	s_add_u32 s22, s22, 0x2000
	s_addc_u32 s23, s23, 0
	global_load_dword v88, v4, s[22:23] offset:-4096
	global_load_dword v89, v4, s[22:23] offset:-2048
	global_load_dword v90, v4, s[22:23] offset:0
	global_load_dword v91, v4, s[22:23] offset:2048
	s_add_u32 s22, s22, 0x2000
	s_addc_u32 s23, s23, 0
	global_load_dword v92, v4, s[22:23] offset:-4096
	global_load_dword v93, v4, s[22:23] offset:-2048
	global_load_dword v94, v4, s[22:23] offset:0
	global_load_dword v95, v4, s[22:23] offset:2048
	s_add_u32 s22, s22, 0x2000
	s_addc_u32 s23, s23, 0
	global_load_dword v104, v4, s[22:23] offset:-4096
	global_load_dword v105, v4, s[22:23] offset:-2048
	global_load_dword v106, v4, s[22:23] offset:0
	global_load_dword v107, v4, s[22:23] offset:2048
	s_add_u32 s22, s22, 0x2000
	s_addc_u32 s23, s23, 0
	global_load_dword v108, v4, s[22:23] offset:-4096
	global_load_dword v109, v4, s[22:23] offset:-2048
	global_load_dword v110, v4, s[22:23] offset:0
	global_load_dword v111, v4, s[22:23] offset:2048
	s_add_u32 s22, s22, 0x2000
	s_addc_u32 s23, s23, 0
	global_load_dword v112, v4, s[22:23] offset:-4096
	global_load_dword v113, v4, s[22:23] offset:-2048
	global_load_dword v114, v4, s[22:23] offset:0
	global_load_dword v115, v4, s[22:23] offset:2048
	s_waitcnt vmcnt(48)
	v_readlane_b32 s20, v8, 0
	v_readlane_b32 s21, v9, 0
	v_readlane_b32 s24, v10, 0
	v_fmac_f32_e32 v3, s20, v44
	v_readlane_b32 s25, v11, 0
	v_fmac_f32_e32 v3, s21, v45
	v_readlane_b32 s20, v8, 1
	v_fmac_f32_e32 v3, s24, v46
	v_readlane_b32 s21, v9, 1
	v_fmac_f32_e32 v3, s25, v47
	v_readlane_b32 s24, v10, 1
	v_fmac_f32_e32 v3, s20, v48
	v_readlane_b32 s25, v11, 1
	v_fmac_f32_e32 v3, s21, v49
	v_readlane_b32 s20, v8, 2
	v_fmac_f32_e32 v3, s24, v50
	v_readlane_b32 s21, v9, 2
	v_fmac_f32_e32 v3, s25, v51
	v_readlane_b32 s24, v10, 2
	v_fmac_f32_e32 v3, s20, v52
	v_readlane_b32 s25, v11, 2
	v_fmac_f32_e32 v3, s21, v53
	v_readlane_b32 s20, v8, 3
	v_fmac_f32_e32 v3, s24, v54
	v_readlane_b32 s21, v9, 3
	v_fmac_f32_e32 v3, s25, v55
	v_readlane_b32 s24, v10, 3
	v_fmac_f32_e32 v3, s20, v56
	v_readlane_b32 s25, v11, 3
	v_fmac_f32_e32 v3, s21, v57
	v_readlane_b32 s20, v8, 4
	v_fmac_f32_e32 v3, s24, v58
	v_readlane_b32 s21, v9, 4
	v_fmac_f32_e32 v3, s25, v59
	v_readlane_b32 s24, v10, 4
	s_add_u32 s22, s22, 0x2000
	s_addc_u32 s23, s23, 0
	global_load_dword v44, v4, s[22:23] offset:-4096
	global_load_dword v45, v4, s[22:23] offset:-2048
	global_load_dword v46, v4, s[22:23] offset:0
	global_load_dword v47, v4, s[22:23] offset:2048
	s_add_u32 s22, s22, 0x2000
	s_addc_u32 s23, s23, 0
	global_load_dword v48, v4, s[22:23] offset:-4096
	global_load_dword v49, v4, s[22:23] offset:-2048
	global_load_dword v50, v4, s[22:23] offset:0
	global_load_dword v51, v4, s[22:23] offset:2048
	s_add_u32 s22, s22, 0x2000
	s_addc_u32 s23, s23, 0
	global_load_dword v52, v4, s[22:23] offset:-4096
	global_load_dword v53, v4, s[22:23] offset:-2048
	global_load_dword v54, v4, s[22:23] offset:0
	global_load_dword v55, v4, s[22:23] offset:2048
	s_add_u32 s22, s22, 0x2000
	s_addc_u32 s23, s23, 0
	global_load_dword v56, v4, s[22:23] offset:-4096
	global_load_dword v57, v4, s[22:23] offset:-2048
	global_load_dword v58, v4, s[22:23] offset:0
	global_load_dword v59, v4, s[22:23] offset:2048
	s_waitcnt vmcnt(48)
	v_fmac_f32_e32 v3, s20, v60
	v_readlane_b32 s25, v11, 4
	v_fmac_f32_e32 v3, s21, v61
	v_readlane_b32 s20, v8, 5
	v_fmac_f32_e32 v3, s24, v62
	v_readlane_b32 s21, v9, 5
	v_fmac_f32_e32 v3, s25, v63
	v_readlane_b32 s24, v10, 5
	v_fmac_f32_e32 v3, s20, v64
	v_readlane_b32 s25, v11, 5
	v_fmac_f32_e32 v3, s21, v65
	v_readlane_b32 s20, v8, 6
	v_fmac_f32_e32 v3, s24, v66
	v_readlane_b32 s21, v9, 6
	v_fmac_f32_e32 v3, s25, v67
	v_readlane_b32 s24, v10, 6
	v_fmac_f32_e32 v3, s20, v68
	v_readlane_b32 s25, v11, 6
	v_fmac_f32_e32 v3, s21, v69
	v_readlane_b32 s20, v8, 7
	v_fmac_f32_e32 v3, s24, v70
	v_readlane_b32 s21, v9, 7
	v_fmac_f32_e32 v3, s25, v71
	v_readlane_b32 s24, v10, 7
	v_fmac_f32_e32 v3, s20, v72
	v_readlane_b32 s25, v11, 7
	v_fmac_f32_e32 v3, s21, v73
	v_readlane_b32 s20, v8, 8
	v_fmac_f32_e32 v3, s24, v74
	v_readlane_b32 s21, v9, 8
	v_fmac_f32_e32 v3, s25, v75
	v_readlane_b32 s24, v10, 8
	s_add_u32 s22, s22, 0x2000
	s_addc_u32 s23, s23, 0
	global_load_dword v60, v4, s[22:23] offset:-4096
	global_load_dword v61, v4, s[22:23] offset:-2048
	global_load_dword v62, v4, s[22:23] offset:0
	global_load_dword v63, v4, s[22:23] offset:2048
	s_add_u32 s22, s22, 0x2000
	s_addc_u32 s23, s23, 0
	global_load_dword v64, v4, s[22:23] offset:-4096
	global_load_dword v65, v4, s[22:23] offset:-2048
	global_load_dword v66, v4, s[22:23] offset:0
	global_load_dword v67, v4, s[22:23] offset:2048
	s_add_u32 s22, s22, 0x2000
	s_addc_u32 s23, s23, 0
	global_load_dword v68, v4, s[22:23] offset:-4096
	global_load_dword v69, v4, s[22:23] offset:-2048
	global_load_dword v70, v4, s[22:23] offset:0
	global_load_dword v71, v4, s[22:23] offset:2048
	s_add_u32 s22, s22, 0x2000
	s_addc_u32 s23, s23, 0
	global_load_dword v72, v4, s[22:23] offset:-4096
	global_load_dword v73, v4, s[22:23] offset:-2048
	global_load_dword v74, v4, s[22:23] offset:0
	global_load_dword v75, v4, s[22:23] offset:2048
	s_waitcnt vmcnt(48)
	v_fmac_f32_e32 v3, s20, v76
	v_readlane_b32 s25, v11, 8
	v_fmac_f32_e32 v3, s21, v77
	v_readlane_b32 s20, v8, 9
	v_fmac_f32_e32 v3, s24, v78
	v_readlane_b32 s21, v9, 9
	v_fmac_f32_e32 v3, s25, v79
	v_readlane_b32 s24, v10, 9
	v_fmac_f32_e32 v3, s20, v80
	v_readlane_b32 s25, v11, 9
	v_fmac_f32_e32 v3, s21, v81
	v_readlane_b32 s20, v8, 10
	v_fmac_f32_e32 v3, s24, v82
	v_readlane_b32 s21, v9, 10
	v_fmac_f32_e32 v3, s25, v83
	v_readlane_b32 s24, v10, 10
	v_fmac_f32_e32 v3, s20, v84
	v_readlane_b32 s25, v11, 10
	v_fmac_f32_e32 v3, s21, v85
	v_readlane_b32 s20, v8, 11
	v_fmac_f32_e32 v3, s24, v86
	v_readlane_b32 s21, v9, 11
	v_fmac_f32_e32 v3, s25, v87
	v_readlane_b32 s24, v10, 11
	v_fmac_f32_e32 v3, s20, v88
	v_readlane_b32 s25, v11, 11
	v_fmac_f32_e32 v3, s21, v89
	v_readlane_b32 s20, v8, 12
	v_fmac_f32_e32 v3, s24, v90
	v_readlane_b32 s21, v9, 12
	v_fmac_f32_e32 v3, s25, v91
	v_readlane_b32 s24, v10, 12
	s_add_u32 s22, s22, 0x2000
	s_addc_u32 s23, s23, 0
	global_load_dword v76, v4, s[22:23] offset:-4096
	global_load_dword v77, v4, s[22:23] offset:-2048
	global_load_dword v78, v4, s[22:23] offset:0
	global_load_dword v79, v4, s[22:23] offset:2048
	s_add_u32 s22, s22, 0x2000
	s_addc_u32 s23, s23, 0
	global_load_dword v80, v4, s[22:23] offset:-4096
	global_load_dword v81, v4, s[22:23] offset:-2048
	global_load_dword v82, v4, s[22:23] offset:0
	global_load_dword v83, v4, s[22:23] offset:2048
	s_add_u32 s22, s22, 0x2000
	s_addc_u32 s23, s23, 0
	global_load_dword v84, v4, s[22:23] offset:-4096
	global_load_dword v85, v4, s[22:23] offset:-2048
	global_load_dword v86, v4, s[22:23] offset:0
	global_load_dword v87, v4, s[22:23] offset:2048
	s_add_u32 s22, s22, 0x2000
	s_addc_u32 s23, s23, 0
	global_load_dword v88, v4, s[22:23] offset:-4096
	global_load_dword v89, v4, s[22:23] offset:-2048
	global_load_dword v90, v4, s[22:23] offset:0
	global_load_dword v91, v4, s[22:23] offset:2048
	s_waitcnt vmcnt(48)
	v_fmac_f32_e32 v3, s20, v92
	v_readlane_b32 s25, v11, 12
	v_fmac_f32_e32 v3, s21, v93
	v_readlane_b32 s20, v8, 13
	v_fmac_f32_e32 v3, s24, v94
	v_readlane_b32 s21, v9, 13
	v_fmac_f32_e32 v3, s25, v95
	v_readlane_b32 s24, v10, 13
	v_fmac_f32_e32 v3, s20, v104
	v_readlane_b32 s25, v11, 13
	v_fmac_f32_e32 v3, s21, v105
	v_readlane_b32 s20, v8, 14
	v_fmac_f32_e32 v3, s24, v106
	v_readlane_b32 s21, v9, 14
	v_fmac_f32_e32 v3, s25, v107
	v_readlane_b32 s24, v10, 14
	v_fmac_f32_e32 v3, s20, v108
	v_readlane_b32 s25, v11, 14
	v_fmac_f32_e32 v3, s21, v109
	v_readlane_b32 s20, v8, 15
	v_fmac_f32_e32 v3, s24, v110
	v_readlane_b32 s21, v9, 15
	v_fmac_f32_e32 v3, s25, v111
	v_readlane_b32 s24, v10, 15
	v_fmac_f32_e32 v3, s20, v112
	v_readlane_b32 s25, v11, 15
	v_fmac_f32_e32 v3, s21, v113
	v_readlane_b32 s20, v8, 16
	v_fmac_f32_e32 v3, s24, v114
	v_readlane_b32 s21, v9, 16
	v_fmac_f32_e32 v3, s25, v115
	v_readlane_b32 s24, v10, 16
	s_add_u32 s22, s22, 0x2000
	s_addc_u32 s23, s23, 0
	global_load_dword v92, v4, s[22:23] offset:-4096
	global_load_dword v93, v4, s[22:23] offset:-2048
	global_load_dword v94, v4, s[22:23] offset:0
	global_load_dword v95, v4, s[22:23] offset:2048
	s_add_u32 s22, s22, 0x2000
	s_addc_u32 s23, s23, 0
	global_load_dword v104, v4, s[22:23] offset:-4096
	global_load_dword v105, v4, s[22:23] offset:-2048
	global_load_dword v106, v4, s[22:23] offset:0
	global_load_dword v107, v4, s[22:23] offset:2048
	s_add_u32 s22, s22, 0x2000
	s_addc_u32 s23, s23, 0
	global_load_dword v108, v4, s[22:23] offset:-4096
	global_load_dword v109, v4, s[22:23] offset:-2048
	global_load_dword v110, v4, s[22:23] offset:0
	global_load_dword v111, v4, s[22:23] offset:2048
	s_add_u32 s22, s22, 0x2000
	s_addc_u32 s23, s23, 0
	global_load_dword v112, v4, s[22:23] offset:-4096
	global_load_dword v113, v4, s[22:23] offset:-2048
	global_load_dword v114, v4, s[22:23] offset:0
	global_load_dword v115, v4, s[22:23] offset:2048
	s_waitcnt vmcnt(48)
	v_fmac_f32_e32 v3, s20, v44
	v_readlane_b32 s25, v11, 16
	v_fmac_f32_e32 v3, s21, v45
	v_readlane_b32 s20, v8, 17
	v_fmac_f32_e32 v3, s24, v46
	v_readlane_b32 s21, v9, 17
	v_fmac_f32_e32 v3, s25, v47
	v_readlane_b32 s24, v10, 17
	v_fmac_f32_e32 v3, s20, v48
	v_readlane_b32 s25, v11, 17
	v_fmac_f32_e32 v3, s21, v49
	v_readlane_b32 s20, v8, 18
	v_fmac_f32_e32 v3, s24, v50
	v_readlane_b32 s21, v9, 18
	v_fmac_f32_e32 v3, s25, v51
	v_readlane_b32 s24, v10, 18
	v_fmac_f32_e32 v3, s20, v52
	v_readlane_b32 s25, v11, 18
	v_fmac_f32_e32 v3, s21, v53
	v_readlane_b32 s20, v8, 19
	v_fmac_f32_e32 v3, s24, v54
	v_readlane_b32 s21, v9, 19
	v_fmac_f32_e32 v3, s25, v55
	v_readlane_b32 s24, v10, 19
	v_fmac_f32_e32 v3, s20, v56
	v_readlane_b32 s25, v11, 19
	v_fmac_f32_e32 v3, s21, v57
	v_readlane_b32 s20, v8, 20
	v_fmac_f32_e32 v3, s24, v58
	v_readlane_b32 s21, v9, 20
	v_fmac_f32_e32 v3, s25, v59
	v_readlane_b32 s24, v10, 20
	s_add_u32 s22, s22, 0x2000
	s_addc_u32 s23, s23, 0
	global_load_dword v44, v4, s[22:23] offset:-4096
	global_load_dword v45, v4, s[22:23] offset:-2048
	global_load_dword v46, v4, s[22:23] offset:0
	global_load_dword v47, v4, s[22:23] offset:2048
	s_add_u32 s22, s22, 0x2000
	s_addc_u32 s23, s23, 0
	global_load_dword v48, v4, s[22:23] offset:-4096
	global_load_dword v49, v4, s[22:23] offset:-2048
	global_load_dword v50, v4, s[22:23] offset:0
	global_load_dword v51, v4, s[22:23] offset:2048
	s_add_u32 s22, s22, 0x2000
	s_addc_u32 s23, s23, 0
	global_load_dword v52, v4, s[22:23] offset:-4096
	global_load_dword v53, v4, s[22:23] offset:-2048
	global_load_dword v54, v4, s[22:23] offset:0
	global_load_dword v55, v4, s[22:23] offset:2048
	s_add_u32 s22, s22, 0x2000
	s_addc_u32 s23, s23, 0
	global_load_dword v56, v4, s[22:23] offset:-4096
	global_load_dword v57, v4, s[22:23] offset:-2048
	global_load_dword v58, v4, s[22:23] offset:0
	global_load_dword v59, v4, s[22:23] offset:2048
	s_waitcnt vmcnt(48)
	v_fmac_f32_e32 v3, s20, v60
	v_readlane_b32 s25, v11, 20
	v_fmac_f32_e32 v3, s21, v61
	v_readlane_b32 s20, v8, 21
	v_fmac_f32_e32 v3, s24, v62
	v_readlane_b32 s21, v9, 21
	v_fmac_f32_e32 v3, s25, v63
	v_readlane_b32 s24, v10, 21
	v_fmac_f32_e32 v3, s20, v64
	v_readlane_b32 s25, v11, 21
	v_fmac_f32_e32 v3, s21, v65
	v_readlane_b32 s20, v8, 22
	v_fmac_f32_e32 v3, s24, v66
	v_readlane_b32 s21, v9, 22
	v_fmac_f32_e32 v3, s25, v67
	v_readlane_b32 s24, v10, 22
	v_fmac_f32_e32 v3, s20, v68
	v_readlane_b32 s25, v11, 22
	v_fmac_f32_e32 v3, s21, v69
	v_readlane_b32 s20, v8, 23
	v_fmac_f32_e32 v3, s24, v70
	v_readlane_b32 s21, v9, 23
	v_fmac_f32_e32 v3, s25, v71
	v_readlane_b32 s24, v10, 23
	v_fmac_f32_e32 v3, s20, v72
	v_readlane_b32 s25, v11, 23
	v_fmac_f32_e32 v3, s21, v73
	v_readlane_b32 s20, v8, 24
	v_fmac_f32_e32 v3, s24, v74
	v_readlane_b32 s21, v9, 24
	v_fmac_f32_e32 v3, s25, v75
	v_readlane_b32 s24, v10, 24
	s_add_u32 s22, s22, 0x2000
	s_addc_u32 s23, s23, 0
	global_load_dword v60, v4, s[22:23] offset:-4096
	global_load_dword v61, v4, s[22:23] offset:-2048
	global_load_dword v62, v4, s[22:23] offset:0
	global_load_dword v63, v4, s[22:23] offset:2048
	s_add_u32 s22, s22, 0x2000
	s_addc_u32 s23, s23, 0
	global_load_dword v64, v4, s[22:23] offset:-4096
	global_load_dword v65, v4, s[22:23] offset:-2048
	global_load_dword v66, v4, s[22:23] offset:0
	global_load_dword v67, v4, s[22:23] offset:2048
	s_add_u32 s22, s22, 0x2000
	s_addc_u32 s23, s23, 0
	global_load_dword v68, v4, s[22:23] offset:-4096
	global_load_dword v69, v4, s[22:23] offset:-2048
	global_load_dword v70, v4, s[22:23] offset:0
	global_load_dword v71, v4, s[22:23] offset:2048
	s_add_u32 s22, s22, 0x2000
	s_addc_u32 s23, s23, 0
	global_load_dword v72, v4, s[22:23] offset:-4096
	global_load_dword v73, v4, s[22:23] offset:-2048
	global_load_dword v74, v4, s[22:23] offset:0
	global_load_dword v75, v4, s[22:23] offset:2048
	s_waitcnt vmcnt(48)
	v_fmac_f32_e32 v3, s20, v76
	v_readlane_b32 s25, v11, 24
	v_fmac_f32_e32 v3, s21, v77
	v_readlane_b32 s20, v8, 25
	v_fmac_f32_e32 v3, s24, v78
	v_readlane_b32 s21, v9, 25
	v_fmac_f32_e32 v3, s25, v79
	v_readlane_b32 s24, v10, 25
	v_fmac_f32_e32 v3, s20, v80
	v_readlane_b32 s25, v11, 25
	v_fmac_f32_e32 v3, s21, v81
	v_readlane_b32 s20, v8, 26
	v_fmac_f32_e32 v3, s24, v82
	v_readlane_b32 s21, v9, 26
	v_fmac_f32_e32 v3, s25, v83
	v_readlane_b32 s24, v10, 26
	v_fmac_f32_e32 v3, s20, v84
	v_readlane_b32 s25, v11, 26
	v_fmac_f32_e32 v3, s21, v85
	v_readlane_b32 s20, v8, 27
	v_fmac_f32_e32 v3, s24, v86
	v_readlane_b32 s21, v9, 27
	v_fmac_f32_e32 v3, s25, v87
	v_readlane_b32 s24, v10, 27
	v_fmac_f32_e32 v3, s20, v88
	v_readlane_b32 s25, v11, 27
	v_fmac_f32_e32 v3, s21, v89
	v_readlane_b32 s20, v8, 28
	v_fmac_f32_e32 v3, s24, v90
	v_readlane_b32 s21, v9, 28
	v_fmac_f32_e32 v3, s25, v91
	v_readlane_b32 s24, v10, 28
	s_add_u32 s22, s22, 0x2000
	s_addc_u32 s23, s23, 0
	global_load_dword v76, v4, s[22:23] offset:-4096
	global_load_dword v77, v4, s[22:23] offset:-2048
	global_load_dword v78, v4, s[22:23] offset:0
	global_load_dword v79, v4, s[22:23] offset:2048
	s_add_u32 s22, s22, 0x2000
	s_addc_u32 s23, s23, 0
	global_load_dword v80, v4, s[22:23] offset:-4096
	global_load_dword v81, v4, s[22:23] offset:-2048
	global_load_dword v82, v4, s[22:23] offset:0
	global_load_dword v83, v4, s[22:23] offset:2048
	s_add_u32 s22, s22, 0x2000
	s_addc_u32 s23, s23, 0
	global_load_dword v84, v4, s[22:23] offset:-4096
	global_load_dword v85, v4, s[22:23] offset:-2048
	global_load_dword v86, v4, s[22:23] offset:0
	global_load_dword v87, v4, s[22:23] offset:2048
	s_add_u32 s22, s22, 0x2000
	s_addc_u32 s23, s23, 0
	global_load_dword v88, v4, s[22:23] offset:-4096
	global_load_dword v89, v4, s[22:23] offset:-2048
	global_load_dword v90, v4, s[22:23] offset:0
	global_load_dword v91, v4, s[22:23] offset:2048
	s_waitcnt vmcnt(48)
	v_fmac_f32_e32 v3, s20, v92
	v_readlane_b32 s25, v11, 28
	v_fmac_f32_e32 v3, s21, v93
	v_readlane_b32 s20, v8, 29
	v_fmac_f32_e32 v3, s24, v94
	v_readlane_b32 s21, v9, 29
	v_fmac_f32_e32 v3, s25, v95
	v_readlane_b32 s24, v10, 29
	v_fmac_f32_e32 v3, s20, v104
	v_readlane_b32 s25, v11, 29
	v_fmac_f32_e32 v3, s21, v105
	v_readlane_b32 s20, v8, 30
	v_fmac_f32_e32 v3, s24, v106
	v_readlane_b32 s21, v9, 30
	v_fmac_f32_e32 v3, s25, v107
	v_readlane_b32 s24, v10, 30
	v_fmac_f32_e32 v3, s20, v108
	v_readlane_b32 s25, v11, 30
	v_fmac_f32_e32 v3, s21, v109
	v_readlane_b32 s20, v8, 31
	v_fmac_f32_e32 v3, s24, v110
	v_readlane_b32 s21, v9, 31
	v_fmac_f32_e32 v3, s25, v111
	v_readlane_b32 s24, v10, 31
	v_fmac_f32_e32 v3, s20, v112
	v_readlane_b32 s25, v11, 31
	v_fmac_f32_e32 v3, s21, v113
	v_readlane_b32 s20, v8, 32
	v_fmac_f32_e32 v3, s24, v114
	v_readlane_b32 s21, v9, 32
	v_fmac_f32_e32 v3, s25, v115
	v_readlane_b32 s24, v10, 32
	s_add_u32 s22, s22, 0x2000
	s_addc_u32 s23, s23, 0
	global_load_dword v92, v4, s[22:23] offset:-4096
	global_load_dword v93, v4, s[22:23] offset:-2048
	global_load_dword v94, v4, s[22:23] offset:0
	global_load_dword v95, v4, s[22:23] offset:2048
	s_add_u32 s22, s22, 0x2000
	s_addc_u32 s23, s23, 0
	global_load_dword v104, v4, s[22:23] offset:-4096
	global_load_dword v105, v4, s[22:23] offset:-2048
	global_load_dword v106, v4, s[22:23] offset:0
	global_load_dword v107, v4, s[22:23] offset:2048
	s_add_u32 s22, s22, 0x2000
	s_addc_u32 s23, s23, 0
	global_load_dword v108, v4, s[22:23] offset:-4096
	global_load_dword v109, v4, s[22:23] offset:-2048
	global_load_dword v110, v4, s[22:23] offset:0
	global_load_dword v111, v4, s[22:23] offset:2048
	s_add_u32 s22, s22, 0x2000
	s_addc_u32 s23, s23, 0
	global_load_dword v112, v4, s[22:23] offset:-4096
	global_load_dword v113, v4, s[22:23] offset:-2048
	global_load_dword v114, v4, s[22:23] offset:0
	global_load_dword v115, v4, s[22:23] offset:2048
	s_waitcnt vmcnt(48)
	v_fmac_f32_e32 v3, s20, v44
	v_readlane_b32 s25, v11, 32
	v_fmac_f32_e32 v3, s21, v45
	v_readlane_b32 s20, v8, 33
	v_fmac_f32_e32 v3, s24, v46
	v_readlane_b32 s21, v9, 33
	v_fmac_f32_e32 v3, s25, v47
	v_readlane_b32 s24, v10, 33
	v_fmac_f32_e32 v3, s20, v48
	v_readlane_b32 s25, v11, 33
	v_fmac_f32_e32 v3, s21, v49
	v_readlane_b32 s20, v8, 34
	v_fmac_f32_e32 v3, s24, v50
	v_readlane_b32 s21, v9, 34
	v_fmac_f32_e32 v3, s25, v51
	v_readlane_b32 s24, v10, 34
	v_fmac_f32_e32 v3, s20, v52
	v_readlane_b32 s25, v11, 34
	v_fmac_f32_e32 v3, s21, v53
	v_readlane_b32 s20, v8, 35
	v_fmac_f32_e32 v3, s24, v54
	v_readlane_b32 s21, v9, 35
	v_fmac_f32_e32 v3, s25, v55
	v_readlane_b32 s24, v10, 35
	v_fmac_f32_e32 v3, s20, v56
	v_readlane_b32 s25, v11, 35
	v_fmac_f32_e32 v3, s21, v57
	v_readlane_b32 s20, v8, 36
	v_fmac_f32_e32 v3, s24, v58
	v_readlane_b32 s21, v9, 36
	v_fmac_f32_e32 v3, s25, v59
	v_readlane_b32 s24, v10, 36
	s_add_u32 s22, s22, 0x2000
	s_addc_u32 s23, s23, 0
	global_load_dword v44, v4, s[22:23] offset:-4096
	global_load_dword v45, v4, s[22:23] offset:-2048
	global_load_dword v46, v4, s[22:23] offset:0
	global_load_dword v47, v4, s[22:23] offset:2048
	s_add_u32 s22, s22, 0x2000
	s_addc_u32 s23, s23, 0
	global_load_dword v48, v4, s[22:23] offset:-4096
	global_load_dword v49, v4, s[22:23] offset:-2048
	global_load_dword v50, v4, s[22:23] offset:0
	global_load_dword v51, v4, s[22:23] offset:2048
	s_add_u32 s22, s22, 0x2000
	s_addc_u32 s23, s23, 0
	global_load_dword v52, v4, s[22:23] offset:-4096
	global_load_dword v53, v4, s[22:23] offset:-2048
	global_load_dword v54, v4, s[22:23] offset:0
	global_load_dword v55, v4, s[22:23] offset:2048
	s_add_u32 s22, s22, 0x2000
	s_addc_u32 s23, s23, 0
	global_load_dword v56, v4, s[22:23] offset:-4096
	global_load_dword v57, v4, s[22:23] offset:-2048
	global_load_dword v58, v4, s[22:23] offset:0
	global_load_dword v59, v4, s[22:23] offset:2048
	s_waitcnt vmcnt(48)
	v_fmac_f32_e32 v3, s20, v60
	v_readlane_b32 s25, v11, 36
	v_fmac_f32_e32 v3, s21, v61
	v_readlane_b32 s20, v8, 37
	v_fmac_f32_e32 v3, s24, v62
	v_readlane_b32 s21, v9, 37
	v_fmac_f32_e32 v3, s25, v63
	v_readlane_b32 s24, v10, 37
	v_fmac_f32_e32 v3, s20, v64
	v_readlane_b32 s25, v11, 37
	v_fmac_f32_e32 v3, s21, v65
	v_readlane_b32 s20, v8, 38
	v_fmac_f32_e32 v3, s24, v66
	v_readlane_b32 s21, v9, 38
	v_fmac_f32_e32 v3, s25, v67
	v_readlane_b32 s24, v10, 38
	v_fmac_f32_e32 v3, s20, v68
	v_readlane_b32 s25, v11, 38
	v_fmac_f32_e32 v3, s21, v69
	v_readlane_b32 s20, v8, 39
	v_fmac_f32_e32 v3, s24, v70
	v_readlane_b32 s21, v9, 39
	v_fmac_f32_e32 v3, s25, v71
	v_readlane_b32 s24, v10, 39
	v_fmac_f32_e32 v3, s20, v72
	v_readlane_b32 s25, v11, 39
	v_fmac_f32_e32 v3, s21, v73
	v_readlane_b32 s20, v8, 40
	v_fmac_f32_e32 v3, s24, v74
	v_readlane_b32 s21, v9, 40
	v_fmac_f32_e32 v3, s25, v75
	v_readlane_b32 s24, v10, 40
	s_add_u32 s22, s22, 0x2000
	s_addc_u32 s23, s23, 0
	global_load_dword v60, v4, s[22:23] offset:-4096
	global_load_dword v61, v4, s[22:23] offset:-2048
	global_load_dword v62, v4, s[22:23] offset:0
	global_load_dword v63, v4, s[22:23] offset:2048
	s_add_u32 s22, s22, 0x2000
	s_addc_u32 s23, s23, 0
	global_load_dword v64, v4, s[22:23] offset:-4096
	global_load_dword v65, v4, s[22:23] offset:-2048
	global_load_dword v66, v4, s[22:23] offset:0
	global_load_dword v67, v4, s[22:23] offset:2048
	s_add_u32 s22, s22, 0x2000
	s_addc_u32 s23, s23, 0
	global_load_dword v68, v4, s[22:23] offset:-4096
	global_load_dword v69, v4, s[22:23] offset:-2048
	global_load_dword v70, v4, s[22:23] offset:0
	global_load_dword v71, v4, s[22:23] offset:2048
	s_add_u32 s22, s22, 0x2000
	s_addc_u32 s23, s23, 0
	global_load_dword v72, v4, s[22:23] offset:-4096
	global_load_dword v73, v4, s[22:23] offset:-2048
	global_load_dword v74, v4, s[22:23] offset:0
	global_load_dword v75, v4, s[22:23] offset:2048
	s_waitcnt vmcnt(48)
	v_fmac_f32_e32 v3, s20, v76
	v_readlane_b32 s25, v11, 40
	v_fmac_f32_e32 v3, s21, v77
	v_readlane_b32 s20, v8, 41
	v_fmac_f32_e32 v3, s24, v78
	v_readlane_b32 s21, v9, 41
	v_fmac_f32_e32 v3, s25, v79
	v_readlane_b32 s24, v10, 41
	v_fmac_f32_e32 v3, s20, v80
	v_readlane_b32 s25, v11, 41
	v_fmac_f32_e32 v3, s21, v81
	v_readlane_b32 s20, v8, 42
	v_fmac_f32_e32 v3, s24, v82
	v_readlane_b32 s21, v9, 42
	v_fmac_f32_e32 v3, s25, v83
	v_readlane_b32 s24, v10, 42
	v_fmac_f32_e32 v3, s20, v84
	v_readlane_b32 s25, v11, 42
	v_fmac_f32_e32 v3, s21, v85
	v_readlane_b32 s20, v8, 43
	v_fmac_f32_e32 v3, s24, v86
	v_readlane_b32 s21, v9, 43
	v_fmac_f32_e32 v3, s25, v87
	v_readlane_b32 s24, v10, 43
	v_fmac_f32_e32 v3, s20, v88
	v_readlane_b32 s25, v11, 43
	v_fmac_f32_e32 v3, s21, v89
	v_readlane_b32 s20, v8, 44
	v_fmac_f32_e32 v3, s24, v90
	v_readlane_b32 s21, v9, 44
	v_fmac_f32_e32 v3, s25, v91
	v_readlane_b32 s24, v10, 44
	s_add_u32 s22, s22, 0x2000
	s_addc_u32 s23, s23, 0
	global_load_dword v76, v4, s[22:23] offset:-4096
	global_load_dword v77, v4, s[22:23] offset:-2048
	global_load_dword v78, v4, s[22:23] offset:0
	global_load_dword v79, v4, s[22:23] offset:2048
	s_add_u32 s22, s22, 0x2000
	s_addc_u32 s23, s23, 0
	global_load_dword v80, v4, s[22:23] offset:-4096
	global_load_dword v81, v4, s[22:23] offset:-2048
	global_load_dword v82, v4, s[22:23] offset:0
	global_load_dword v83, v4, s[22:23] offset:2048
	s_add_u32 s22, s22, 0x2000
	s_addc_u32 s23, s23, 0
	global_load_dword v84, v4, s[22:23] offset:-4096
	global_load_dword v85, v4, s[22:23] offset:-2048
	global_load_dword v86, v4, s[22:23] offset:0
	global_load_dword v87, v4, s[22:23] offset:2048
	s_add_u32 s22, s22, 0x2000
	s_addc_u32 s23, s23, 0
	global_load_dword v88, v4, s[22:23] offset:-4096
	global_load_dword v89, v4, s[22:23] offset:-2048
	global_load_dword v90, v4, s[22:23] offset:0
	global_load_dword v91, v4, s[22:23] offset:2048
	s_waitcnt vmcnt(48)
	v_fmac_f32_e32 v3, s20, v92
	v_readlane_b32 s25, v11, 44
	v_fmac_f32_e32 v3, s21, v93
	v_readlane_b32 s20, v8, 45
	v_fmac_f32_e32 v3, s24, v94
	v_readlane_b32 s21, v9, 45
	v_fmac_f32_e32 v3, s25, v95
	v_readlane_b32 s24, v10, 45
	v_fmac_f32_e32 v3, s20, v104
	v_readlane_b32 s25, v11, 45
	v_fmac_f32_e32 v3, s21, v105
	v_readlane_b32 s20, v8, 46
	v_fmac_f32_e32 v3, s24, v106
	v_readlane_b32 s21, v9, 46
	v_fmac_f32_e32 v3, s25, v107
	v_readlane_b32 s24, v10, 46
	v_fmac_f32_e32 v3, s20, v108
	v_readlane_b32 s25, v11, 46
	v_fmac_f32_e32 v3, s21, v109
	v_readlane_b32 s20, v8, 47
	v_fmac_f32_e32 v3, s24, v110
	v_readlane_b32 s21, v9, 47
	v_fmac_f32_e32 v3, s25, v111
	v_readlane_b32 s24, v10, 47
	v_fmac_f32_e32 v3, s20, v112
	v_readlane_b32 s25, v11, 47
	v_fmac_f32_e32 v3, s21, v113
	v_readlane_b32 s20, v8, 48
	v_fmac_f32_e32 v3, s24, v114
	v_readlane_b32 s21, v9, 48
	v_fmac_f32_e32 v3, s25, v115
	v_readlane_b32 s24, v10, 48
	s_add_u32 s22, s22, 0x2000
	s_addc_u32 s23, s23, 0
	global_load_dword v92, v4, s[22:23] offset:-4096
	global_load_dword v93, v4, s[22:23] offset:-2048
	global_load_dword v94, v4, s[22:23] offset:0
	global_load_dword v95, v4, s[22:23] offset:2048
	s_add_u32 s22, s22, 0x2000
	s_addc_u32 s23, s23, 0
	global_load_dword v104, v4, s[22:23] offset:-4096
	global_load_dword v105, v4, s[22:23] offset:-2048
	global_load_dword v106, v4, s[22:23] offset:0
	global_load_dword v107, v4, s[22:23] offset:2048
	s_add_u32 s22, s22, 0x2000
	s_addc_u32 s23, s23, 0
	global_load_dword v108, v4, s[22:23] offset:-4096
	global_load_dword v109, v4, s[22:23] offset:-2048
	global_load_dword v110, v4, s[22:23] offset:0
	global_load_dword v111, v4, s[22:23] offset:2048
	s_add_u32 s22, s22, 0x2000
	s_addc_u32 s23, s23, 0
	global_load_dword v112, v4, s[22:23] offset:-4096
	global_load_dword v113, v4, s[22:23] offset:-2048
	global_load_dword v114, v4, s[22:23] offset:0
	global_load_dword v115, v4, s[22:23] offset:2048
	s_waitcnt vmcnt(48)
	v_fmac_f32_e32 v3, s20, v44
	v_readlane_b32 s25, v11, 48
	v_fmac_f32_e32 v3, s21, v45
	v_readlane_b32 s20, v8, 49
	v_fmac_f32_e32 v3, s24, v46
	v_readlane_b32 s21, v9, 49
	v_fmac_f32_e32 v3, s25, v47
	v_readlane_b32 s24, v10, 49
	v_fmac_f32_e32 v3, s20, v48
	v_readlane_b32 s25, v11, 49
	v_fmac_f32_e32 v3, s21, v49
	v_readlane_b32 s20, v8, 50
	v_fmac_f32_e32 v3, s24, v50
	v_readlane_b32 s21, v9, 50
	v_fmac_f32_e32 v3, s25, v51
	v_readlane_b32 s24, v10, 50
	v_fmac_f32_e32 v3, s20, v52
	v_readlane_b32 s25, v11, 50
	v_fmac_f32_e32 v3, s21, v53
	v_readlane_b32 s20, v8, 51
	v_fmac_f32_e32 v3, s24, v54
	v_readlane_b32 s21, v9, 51
	v_fmac_f32_e32 v3, s25, v55
	v_readlane_b32 s24, v10, 51
	v_fmac_f32_e32 v3, s20, v56
	v_readlane_b32 s25, v11, 51
	v_fmac_f32_e32 v3, s21, v57
	v_readlane_b32 s20, v8, 52
	v_fmac_f32_e32 v3, s24, v58
	v_readlane_b32 s21, v9, 52
	v_fmac_f32_e32 v3, s25, v59
	v_readlane_b32 s24, v10, 52
	s_waitcnt vmcnt(32)
	v_fmac_f32_e32 v3, s20, v60
	v_readlane_b32 s25, v11, 52
	v_fmac_f32_e32 v3, s21, v61
	v_readlane_b32 s20, v8, 53
	v_fmac_f32_e32 v3, s24, v62
	v_readlane_b32 s21, v9, 53
	v_fmac_f32_e32 v3, s25, v63
	v_readlane_b32 s24, v10, 53
	v_fmac_f32_e32 v3, s20, v64
	v_readlane_b32 s25, v11, 53
	v_fmac_f32_e32 v3, s21, v65
	v_readlane_b32 s20, v8, 54
	v_fmac_f32_e32 v3, s24, v66
	v_readlane_b32 s21, v9, 54
	v_fmac_f32_e32 v3, s25, v67
	v_readlane_b32 s24, v10, 54
	v_fmac_f32_e32 v3, s20, v68
	v_readlane_b32 s25, v11, 54
	v_fmac_f32_e32 v3, s21, v69
	v_readlane_b32 s20, v8, 55
	v_fmac_f32_e32 v3, s24, v70
	v_readlane_b32 s21, v9, 55
	v_fmac_f32_e32 v3, s25, v71
	v_readlane_b32 s24, v10, 55
	v_fmac_f32_e32 v3, s20, v72
	v_readlane_b32 s25, v11, 55
	v_fmac_f32_e32 v3, s21, v73
	v_readlane_b32 s20, v8, 56
	v_fmac_f32_e32 v3, s24, v74
	v_readlane_b32 s21, v9, 56
	v_fmac_f32_e32 v3, s25, v75
	v_readlane_b32 s24, v10, 56
	s_waitcnt vmcnt(16)
	v_fmac_f32_e32 v3, s20, v76
	v_readlane_b32 s25, v11, 56
	v_fmac_f32_e32 v3, s21, v77
	v_readlane_b32 s20, v8, 57
	v_fmac_f32_e32 v3, s24, v78
	v_readlane_b32 s21, v9, 57
	v_fmac_f32_e32 v3, s25, v79
	v_readlane_b32 s24, v10, 57
	v_fmac_f32_e32 v3, s20, v80
	v_readlane_b32 s25, v11, 57
	v_fmac_f32_e32 v3, s21, v81
	v_readlane_b32 s20, v8, 58
	v_fmac_f32_e32 v3, s24, v82
	v_readlane_b32 s21, v9, 58
	v_fmac_f32_e32 v3, s25, v83
	v_readlane_b32 s24, v10, 58
	v_fmac_f32_e32 v3, s20, v84
	v_readlane_b32 s25, v11, 58
	v_fmac_f32_e32 v3, s21, v85
	v_readlane_b32 s20, v8, 59
	v_fmac_f32_e32 v3, s24, v86
	v_readlane_b32 s21, v9, 59
	v_fmac_f32_e32 v3, s25, v87
	v_readlane_b32 s24, v10, 59
	v_fmac_f32_e32 v3, s20, v88
	v_readlane_b32 s25, v11, 59
	v_fmac_f32_e32 v3, s21, v89
	v_readlane_b32 s20, v8, 60
	v_fmac_f32_e32 v3, s24, v90
	v_readlane_b32 s21, v9, 60
	v_fmac_f32_e32 v3, s25, v91
	v_readlane_b32 s24, v10, 60
	s_waitcnt vmcnt(0)
	v_fmac_f32_e32 v3, s20, v92
	v_readlane_b32 s25, v11, 60
	v_fmac_f32_e32 v3, s21, v93
	v_readlane_b32 s20, v8, 61
	v_fmac_f32_e32 v3, s24, v94
	v_readlane_b32 s21, v9, 61
	v_fmac_f32_e32 v3, s25, v95
	v_readlane_b32 s24, v10, 61
	v_fmac_f32_e32 v3, s20, v104
	v_readlane_b32 s25, v11, 61
	v_fmac_f32_e32 v3, s21, v105
	v_readlane_b32 s20, v8, 62
	v_fmac_f32_e32 v3, s24, v106
	v_readlane_b32 s21, v9, 62
	v_fmac_f32_e32 v3, s25, v107
	v_readlane_b32 s24, v10, 62
	v_fmac_f32_e32 v3, s20, v108
	v_readlane_b32 s25, v11, 62
	v_fmac_f32_e32 v3, s21, v109
	v_readlane_b32 s20, v8, 63
	v_fmac_f32_e32 v3, s24, v110
	v_readlane_b32 s21, v9, 63
	v_fmac_f32_e32 v3, s25, v111
	v_readlane_b32 s24, v10, 63
	v_fmac_f32_e32 v3, s20, v112
	v_readlane_b32 s25, v11, 63
	v_fmac_f32_e32 v3, s21, v113
	v_fmac_f32_e32 v3, s24, v114
	v_fmac_f32_e32 v3, s25, v115
	s_and_b32 s7, s19, 15
	s_lshl_b32 s8, s19, 2
	s_and_b32 s8, s8, 0x1c0
	s_lshl_b32 s6, s6, 13
	s_lshl_b32 s7, s7, 9
	v_or_b32_e32 v4, s8, v1
	s_or_b32 s6, s6, s7
	v_or_b32_e32 v6, s6, v4
	v_ashrrev_i32_e32 v7, 31, v6
	s_add_i32 s19, s19, s4
	s_sub_i32 s5, s5, s4
	s_add_i32 s12, s12, s13
	v_lshl_add_u64 v[6:7], v[6:7], 2, s[0:1]
	s_cmpk_gt_i32 s19, 0xff
	flat_store_dword v[6:7], v3
	s_cbranch_scc0 .LBB0_430
